# attention unit epilogue: xor-1/2/4/8 sum-of-squares shuffles done with DPP adds instead of ds_bpermute round trips (bit-identical)
# speedup vs baseline: 1.0126x; 1.0011x over previous
; __device__ __forceinline__ unsigned f2bf(float f) { unsigned u = __builtin_bit_cast(unsigned, f); return (u + 0x7fffu + ((u >> 16) & 1u)) >> 16; }
; template <bool SAMPLE> __device__ __forceinline__ void attn_unit16(const Ctx& c, LAS unsigned char* lds, int b, int h, int qb, int wave_s) {
;     ...
;             for (int i = 0; i < 4; ++i) {
;                 float ss = 0.f;
; #pragma unroll
;                 for (int et = 0; et < 8; ++et) { o[qt][et][i] -= X[(g * 64 + qt * 32 + et * 4 + i) * 64 + lane2]; ss += o[qt][et][i] * o[qt][et][i]; }
;                 ss += __shfl_xor(ss, 1); ss += __shfl_xor(ss, 2); ss += __shfl_xor(ss, 4); ss += __shfl_xor(ss, 8);
;                 const float rstd = 1.f / sqrtf(ss * (1.f / 128.f) + 1e-5f);
;                 const int ql = 16 * qt + 4 * q4b + i;
;                 const size_t row = SAMPLE ? (size_t)ROW_S0 + b * 16 + ql : (size_t)b * SEQ + tq0 + ql;
; #pragma unroll
;                 for (int et = 0; et < 8; ++et) Y[row * D + h * 128 + 16 * et + c16b] = (bf16)f2bf(o[qt][et][i] * rstd * sg[et]);
.LBB0_886:
	s_andn2_b64 vcc, exec, s[2:3]
	s_waitcnt lgkmcnt(0)
	s_barrier
	s_cbranch_vccnz .LBB0_888
	s_lshl_b32 s0, s63, 14
	v_and_b32_e32 v49, 15, v7
	s_add_i32 s0, s0, 0
	v_lshlrev_b32_e32 v10, 2, v49
	v_lshl_add_u32 v64, v6, 2, s0
	ds_read2st64_b32 v[6:7], v64 offset1:1
	ds_read2st64_b32 v[8:9], v64 offset0:4 offset1:5
	global_load_dword v50, v10, s[26:27]
	global_load_dword v51, v10, s[26:27] offset:64
	global_load_dword v53, v10, s[26:27] offset:128
	global_load_dword v65, v10, s[26:27] offset:192
	global_load_dword v71, v10, s[26:27] offset:256
	global_load_dword v83, v10, s[26:27] offset:320
	global_load_dword v100, v10, s[26:27] offset:384
	global_load_dword v101, v10, s[26:27] offset:448
	ds_read2st64_b32 v[10:11], v64 offset0:6 offset1:7
	ds_read2st64_b32 v[12:13], v64 offset0:2 offset1:3
	ds_read2st64_b32 v[66:67], v64 offset0:8 offset1:9
	s_waitcnt lgkmcnt(4)
	v_sub_f32_e32 v6, v14, v6
	s_waitcnt lgkmcnt(3)
	v_sub_f32_e32 v8, v15, v8
	ds_read2st64_b32 v[76:77], v64 offset0:12 offset1:13
	ds_read2st64_b32 v[14:15], v64 offset0:14 offset1:15
	ds_read2st64_b32 v[16:17], v64 offset0:10 offset1:11
	ds_read2st64_b32 v[78:79], v64 offset0:16 offset1:17
	v_mul_f32_e32 v54, v8, v8
	s_waitcnt lgkmcnt(4)
	v_sub_f32_e32 v66, v19, v66
	s_waitcnt lgkmcnt(3)
	v_sub_f32_e32 v76, v18, v76
	ds_read2st64_b32 v[90:91], v64 offset0:20 offset1:21
	ds_read2st64_b32 v[18:19], v64 offset0:22 offset1:23
	ds_read2st64_b32 v[20:21], v64 offset0:18 offset1:19
	ds_read2st64_b32 v[96:97], v64 offset0:24 offset1:25
	v_fmac_f32_e32 v54, v6, v6
	v_fmac_f32_e32 v54, v66, v66
	v_fmac_f32_e32 v54, v76, v76
	s_waitcnt lgkmcnt(4)
	v_sub_f32_e32 v78, v5, v78
	ds_read2st64_b32 v[98:99], v64 offset0:28 offset1:29
	ds_read2st64_b32 v[22:23], v64 offset0:30 offset1:31
	ds_read2st64_b32 v[24:25], v64 offset0:26 offset1:27
	v_fmac_f32_e32 v54, v78, v78
	s_waitcnt lgkmcnt(6)
	v_sub_f32_e32 v90, v3, v90
	v_fmac_f32_e32 v54, v90, v90
	s_waitcnt lgkmcnt(3)
	v_sub_f32_e32 v96, v2, v96
	v_fmac_f32_e32 v54, v96, v96
	s_waitcnt lgkmcnt(2)
	v_sub_f32_e32 v98, v0, v98
	v_fmac_f32_e32 v54, v98, v98
	v_or_b32_e32 v4, s62, v4
	v_sub_f32_e32 v9, v114, v9
	v_sub_f32_e32 v67, v112, v67
	v_sub_f32_e32 v10, v92, v10
	s_waitcnt lgkmcnt(0)
	s_nop 1
	v_add_f32_dpp v0, v54, v54 quad_perm:[1,0,3,2] row_mask:0xf bank_mask:0xf
	v_sub_f32_e32 v12, v89, v12
	v_sub_f32_e32 v16, v88, v16
	v_sub_f32_e32 v14, v87, v14
	v_sub_f32_e32 v20, v86, v20
	s_waitcnt lgkmcnt(0)
	s_nop 1
	v_add_f32_dpp v0, v0, v0 quad_perm:[2,3,0,1] row_mask:0xf bank_mask:0xf
	v_sub_f32_e32 v18, v85, v18
	v_sub_f32_e32 v24, v84, v24
	v_sub_f32_e32 v22, v82, v22
	v_sub_f32_e32 v11, v81, v11
	s_waitcnt lgkmcnt(0)
	s_nop 1
	v_add_f32_dpp v0, v0, v0 row_half_mirror row_mask:0xf bank_mask:0xf
	v_sub_f32_e32 v15, v74, v15
	s_waitcnt lgkmcnt(0)
	s_nop 1
	v_add_f32_dpp v0, v0, v0 row_mirror row_mask:0xf bank_mask:0xf
	v_fmamk_f32 v0, v0, 0x3c000000, v205
	v_mul_f32_e32 v2, 0x4f800000, v0
	v_cmp_gt_f32_e32 vcc, s75, v0
	s_nop 1
	v_cndmask_b32_e32 v5, v0, v2, vcc
	v_sqrt_f32_e32 v54, v5
	v_lshlrev_b32_e32 v0, 1, v49
	v_lshl_add_u64 v[2:3], s[40:41], 0, v[0:1]
	v_add_u32_e32 v0, -1, v54
	v_add_u32_e32 v49, 1, v54
	v_fma_f32 v55, -v0, v54, v5
	v_fma_f32 v62, -v49, v54, v5
	v_cmp_ge_f32_e64 s[0:1], 0, v55
	s_waitcnt vmcnt(6)
	v_mul_f32_e32 v55, 0x3f4ccccd, v51
	v_cndmask_b32_e64 v0, v54, v0, s[0:1]
	v_cmp_lt_f32_e64 s[0:1], 0, v62
	s_waitcnt vmcnt(5)
	v_mul_f32_e32 v54, 0x3f4ccccd, v53
	s_waitcnt vmcnt(4)
	v_mul_f32_e32 v53, 0x3f4ccccd, v65
	v_cndmask_b32_e64 v0, v0, v49, s[0:1]
	v_mul_f32_e32 v49, 0x37800000, v0
	v_cndmask_b32_e32 v0, v0, v49, vcc
	v_cmp_class_f32_e32 vcc, v5, v206
	s_waitcnt vmcnt(3)
	v_mul_f32_e32 v51, 0x3f4ccccd, v71
	v_mul_f32_e32 v62, 0x3f4ccccd, v50
	v_cndmask_b32_e32 v5, v0, v5, vcc
	v_div_scale_f32 v102, s[0:1], v5, v5, 1.0
	v_rcp_f32_e32 v103, v102
	s_waitcnt vmcnt(2)
	v_mul_f32_e32 v50, 0x3f4ccccd, v83
	s_waitcnt vmcnt(1)
	v_mul_f32_e32 v49, 0x3f4ccccd, v100
	s_waitcnt vmcnt(0)
	v_mul_f32_e32 v0, 0x3f4ccccd, v101
	v_fma_f32 v65, -v102, v103, 1.0
	v_fmac_f32_e32 v103, v65, v103
	v_div_scale_f32 v65, vcc, 1.0, v5, 1.0
	v_mul_f32_e32 v71, v65, v103
	v_fma_f32 v83, -v102, v71, v65
	v_fmac_f32_e32 v71, v83, v103
	v_fma_f32 v65, -v102, v71, v65
	v_div_fmas_f32 v65, v65, v103, v71
	v_div_fixup_f32 v65, v65, v5, 1.0
	v_mul_f32_e32 v6, v6, v65
	v_mov_b32_e32 v5, s17
	v_mul_f32_e32 v6, v62, v6
	v_lshlrev_b64 v[100:101], 11, v[4:5]
	v_bfe_u32 v71, v6, 16, 1
	v_lshl_add_u64 v[100:101], v[2:3], 0, v[100:101]
	v_add3_u32 v6, v6, v71, s76
	global_store_short_d16_hi v[100:101], v6, off
	v_mul_f32_e32 v6, v8, v65
	v_mul_f32_e32 v6, v55, v6
	v_bfe_u32 v8, v6, 16, 1
	v_add3_u32 v6, v6, v8, s76
	global_store_short_d16_hi v[100:101], v6, off offset:32
	v_mul_f32_e32 v6, v66, v65
	v_mul_f32_e32 v6, v54, v6
	v_sub_f32_e32 v66, v113, v7
	v_mul_f32_e32 v7, v9, v9
	v_bfe_u32 v8, v6, 16, 1
	v_fmac_f32_e32 v7, v66, v66
	v_add3_u32 v6, v6, v8, s76
	v_fmac_f32_e32 v7, v67, v67
	v_sub_f32_e32 v71, v105, v77
	global_store_short_d16_hi v[100:101], v6, off offset:64
	v_mul_f32_e32 v6, v76, v65
	v_fmac_f32_e32 v7, v71, v71
	v_sub_f32_e32 v76, v104, v79
	v_fmac_f32_e32 v7, v76, v76
	v_sub_f32_e32 v77, v95, v91
	v_fmac_f32_e32 v7, v77, v77
	v_sub_f32_e32 v79, v94, v97
	v_fmac_f32_e32 v7, v79, v79
	v_sub_f32_e32 v83, v93, v99
	v_fmac_f32_e32 v7, v83, v83
	ds_bpermute_b32 v91, v210, v7
	v_mul_f32_e32 v6, v53, v6
	v_bfe_u32 v8, v6, 16, 1
	v_add3_u32 v6, v6, v8, s76
	global_store_short_d16_hi v[100:101], v6, off offset:96
	s_waitcnt lgkmcnt(0)
	v_add_f32_e32 v7, v7, v91
	v_mul_f32_e32 v6, v78, v65
	v_mul_f32_e32 v6, v51, v6
	v_bfe_u32 v78, v6, 16, 1
	v_add3_u32 v6, v6, v78, s76
	s_waitcnt lgkmcnt(0)
; __device__ __forceinline__ unsigned f2bf(float f) { unsigned u = __builtin_bit_cast(unsigned, f); return (u + 0x7fffu + ((u >> 16) & 1u)) >> 16; }
; template <bool SAMPLE> __device__ __forceinline__ void attn_unit16(const Ctx& c, LAS unsigned char* lds, int b, int h, int qb, int wave_s) {
;     ...
;             for (int i = 0; i < 4; ++i) {
;                 float ss = 0.f;
; #pragma unroll
;                 for (int et = 0; et < 8; ++et) { o[qt][et][i] -= X[(g * 64 + qt * 32 + et * 4 + i) * 64 + lane2]; ss += o[qt][et][i] * o[qt][et][i]; }
;                 ss += __shfl_xor(ss, 1); ss += __shfl_xor(ss, 2); ss += __shfl_xor(ss, 4); ss += __shfl_xor(ss, 8);
;                 const float rstd = 1.f / sqrtf(ss * (1.f / 128.f) + 1e-5f);
;                 const int ql = 16 * qt + 4 * q4b + i;
;                 const size_t row = SAMPLE ? (size_t)ROW_S0 + b * 16 + ql : (size_t)b * SEQ + tq0 + ql;
; #pragma unroll
;                 for (int et = 0; et < 8; ++et) Y[row * D + h * 128 + 16 * et + c16b] = (bf16)f2bf(o[qt][et][i] * rstd * sg[et]);
	s_nop 1
	v_add_f32_dpp v7, v7, v7 quad_perm:[2,3,0,1] row_mask:0xf bank_mask:0xf
	global_store_short_d16_hi v[100:101], v6, off offset:128
	v_mul_f32_e32 v6, v90, v65
	v_mul_f32_e32 v6, v50, v6
	v_bfe_u32 v78, v6, 16, 1
	v_add3_u32 v6, v6, v78, s76
	global_store_short_d16_hi v[100:101], v6, off offset:160
	s_waitcnt lgkmcnt(0)
	s_nop 1
	v_add_f32_dpp v6, v7, v7 row_half_mirror row_mask:0xf bank_mask:0xf
	v_mul_f32_e32 v8, v96, v65
	v_mul_f32_e32 v8, v49, v8
	v_bfe_u32 v78, v8, 16, 1
	v_add3_u32 v8, v8, v78, s76
	s_waitcnt lgkmcnt(0)
	s_nop 1
	v_add_f32_dpp v6, v6, v6 row_mirror row_mask:0xf bank_mask:0xf
	v_fmamk_f32 v6, v6, 0x3c000000, v205
	v_mul_f32_e32 v7, 0x4f800000, v6
	v_cmp_gt_f32_e32 vcc, s75, v6
	global_store_short_d16_hi v[100:101], v8, off offset:192
	v_mul_f32_e32 v8, v98, v65
	v_cndmask_b32_e32 v6, v6, v7, vcc
	v_sqrt_f32_e32 v7, v6
	v_mul_f32_e32 v8, v0, v8
	v_add_u32_e32 v65, -1, v7
	v_fma_f32 v78, -v65, v7, v6
	v_cmp_ge_f32_e64 s[0:1], 0, v78
	v_add_u32_e32 v78, 1, v7
	s_nop 0
	v_cndmask_b32_e64 v65, v7, v65, s[0:1]
	v_fma_f32 v7, -v78, v7, v6
	v_cmp_lt_f32_e64 s[0:1], 0, v7
	s_nop 1
	v_cndmask_b32_e64 v7, v65, v78, s[0:1]
	v_mul_f32_e32 v65, 0x37800000, v7
	v_cndmask_b32_e32 v7, v7, v65, vcc
	v_cmp_class_f32_e32 vcc, v6, v206
	v_bfe_u32 v78, v8, 16, 1
	v_add3_u32 v8, v8, v78, s76
	v_cndmask_b32_e32 v6, v7, v6, vcc
	v_div_scale_f32 v7, s[0:1], v6, v6, 1.0
	v_rcp_f32_e32 v65, v7
	global_store_short_d16_hi v[100:101], v8, off offset:224
	v_fma_f32 v8, -v7, v65, 1.0
	v_fmac_f32_e32 v65, v8, v65
	v_div_scale_f32 v8, vcc, 1.0, v6, 1.0
	v_mul_f32_e32 v78, v8, v65
	v_fma_f32 v90, -v7, v78, v8
	v_fmac_f32_e32 v78, v90, v65
	v_fma_f32 v7, -v7, v78, v8
	v_div_fmas_f32 v7, v7, v65, v78
	v_div_fixup_f32 v8, v7, v6, 1.0
	v_mul_f32_e32 v65, v66, v8
	v_mul_f32_e32 v65, v62, v65
	v_bfe_u32 v66, v65, 16, 1
	v_add3_u32 v65, v65, v66, s76
	v_mul_f32_e32 v66, v10, v10
	v_or_b32_e32 v6, 1, v4
	v_mov_b32_e32 v7, s17
	v_fmac_f32_e32 v66, v12, v12
	v_lshlrev_b64 v[6:7], 11, v[6:7]
	v_mul_f32_e32 v9, v9, v8
	v_fmac_f32_e32 v66, v16, v16
	v_lshl_add_u64 v[6:7], v[2:3], 0, v[6:7]
	v_mul_f32_e32 v9, v55, v9
	v_fmac_f32_e32 v66, v14, v14
	global_store_short_d16_hi v[6:7], v65, off
	v_bfe_u32 v65, v9, 16, 1
	v_fmac_f32_e32 v66, v20, v20
	v_add3_u32 v9, v9, v65, s76
	v_fmac_f32_e32 v66, v18, v18
	global_store_short_d16_hi v[6:7], v9, off offset:32
	v_mul_f32_e32 v9, v67, v8
	v_fmac_f32_e32 v66, v24, v24
	v_mul_f32_e32 v9, v54, v9
	v_fmac_f32_e32 v66, v22, v22
	v_bfe_u32 v65, v9, 16, 1
	v_add3_u32 v9, v9, v65, s76
	global_store_short_d16_hi v[6:7], v9, off offset:64
	v_mul_f32_e32 v9, v71, v8
	v_mul_f32_e32 v9, v53, v9
	v_bfe_u32 v65, v9, 16, 1
	v_add3_u32 v9, v9, v65, s76
	s_waitcnt lgkmcnt(0)
	s_nop 1
	v_add_f32_dpp v65, v66, v66 quad_perm:[1,0,3,2] row_mask:0xf bank_mask:0xf
	global_store_short_d16_hi v[6:7], v9, off offset:96
	v_mul_f32_e32 v9, v76, v8
	v_mul_f32_e32 v9, v51, v9
	v_bfe_u32 v67, v9, 16, 1
	s_waitcnt lgkmcnt(0)
	s_nop 1
	v_add_f32_dpp v65, v65, v65 quad_perm:[2,3,0,1] row_mask:0xf bank_mask:0xf
	v_add3_u32 v9, v9, v67, s76
	global_store_short_d16_hi v[6:7], v9, off offset:128
	v_mul_f32_e32 v9, v77, v8
	v_mul_f32_e32 v9, v50, v9
	v_bfe_u32 v67, v9, 16, 1
	v_add3_u32 v9, v9, v67, s76
	global_store_short_d16_hi v[6:7], v9, off offset:160
	s_waitcnt lgkmcnt(0)
	s_nop 1
	v_add_f32_dpp v9, v65, v65 row_half_mirror row_mask:0xf bank_mask:0xf
	v_mul_f32_e32 v66, v79, v8
	v_mul_f32_e32 v66, v49, v66
	v_bfe_u32 v67, v66, 16, 1
	v_add3_u32 v66, v66, v67, s76
	s_waitcnt lgkmcnt(0)
	s_nop 1
	v_add_f32_dpp v9, v9, v9 row_mirror row_mask:0xf bank_mask:0xf
	v_fmamk_f32 v9, v9, 0x3c000000, v205
	v_mul_f32_e32 v65, 0x4f800000, v9
	v_cmp_gt_f32_e32 vcc, s75, v9
	global_store_short_d16_hi v[6:7], v66, off offset:192
	v_mul_f32_e32 v8, v83, v8
	v_cndmask_b32_e32 v9, v9, v65, vcc
	v_sqrt_f32_e32 v65, v9
	v_mul_f32_e32 v8, v0, v8
	v_sub_f32_e32 v76, v72, v19
	v_sub_f32_e32 v77, v70, v25
	v_add_u32_e32 v66, -1, v65
	v_fma_f32 v67, -v66, v65, v9
	v_cmp_ge_f32_e64 s[0:1], 0, v67
	v_add_u32_e32 v67, 1, v65
	v_sub_f32_e32 v78, v69, v23
	v_cndmask_b32_e64 v66, v65, v66, s[0:1]
	v_fma_f32 v65, -v67, v65, v9
	v_cmp_lt_f32_e64 s[0:1], 0, v65
	s_nop 1
	v_cndmask_b32_e64 v65, v66, v67, s[0:1]
	v_mul_f32_e32 v66, 0x37800000, v65
	v_cndmask_b32_e32 v65, v65, v66, vcc
	v_cmp_class_f32_e32 vcc, v9, v206
	v_bfe_u32 v67, v8, 16, 1
	v_add3_u32 v8, v8, v67, s76
	v_cndmask_b32_e32 v9, v65, v9, vcc
	v_div_scale_f32 v65, s[0:1], v9, v9, 1.0
	v_rcp_f32_e32 v66, v65
	global_store_short_d16_hi v[6:7], v8, off offset:224
	v_fma_f32 v6, -v65, v66, 1.0
	v_fmac_f32_e32 v66, v6, v66
	v_div_scale_f32 v6, vcc, 1.0, v9, 1.0
	v_mul_f32_e32 v7, v6, v66
	v_fma_f32 v8, -v65, v7, v6
	v_fmac_f32_e32 v7, v8, v66
	v_fma_f32 v6, -v65, v7, v6
	v_div_fmas_f32 v6, v6, v66, v7
	v_div_fixup_f32 v8, v6, v9, 1.0
	v_mul_f32_e32 v9, v12, v8
	v_or_b32_e32 v6, 2, v4
	v_mov_b32_e32 v7, s17
	v_mul_f32_e32 v9, v62, v9
	v_lshlrev_b64 v[6:7], 11, v[6:7]
	v_bfe_u32 v12, v9, 16, 1
	v_lshl_add_u64 v[6:7], v[2:3], 0, v[6:7]
	v_add3_u32 v9, v9, v12, s76
	global_store_short_d16_hi v[6:7], v9, off
	v_mul_f32_e32 v9, v10, v8
	v_mul_f32_e32 v9, v55, v9
	v_bfe_u32 v10, v9, 16, 1
	v_add3_u32 v9, v9, v10, s76
	global_store_short_d16_hi v[6:7], v9, off offset:32
	v_mul_f32_e32 v9, v16, v8
	v_mul_f32_e32 v9, v54, v9
	v_bfe_u32 v10, v9, 16, 1
	v_add3_u32 v9, v9, v10, s76
	v_sub_f32_e32 v12, v80, v13
	v_mul_f32_e32 v13, v11, v11
	global_store_short_d16_hi v[6:7], v9, off offset:64
	v_mul_f32_e32 v9, v14, v8
	v_fmac_f32_e32 v13, v12, v12
	v_sub_f32_e32 v14, v75, v17
	v_fmac_f32_e32 v13, v14, v14
	v_fmac_f32_e32 v13, v15, v15
	v_sub_f32_e32 v65, v73, v21
	v_fmac_f32_e32 v13, v65, v65
	v_fmac_f32_e32 v13, v76, v76
	v_fmac_f32_e32 v13, v77, v77
	v_fmac_f32_e32 v13, v78, v78
	v_mul_f32_e32 v9, v53, v9
	v_bfe_u32 v10, v9, 16, 1
	v_add3_u32 v9, v9, v10, s76
	global_store_short_d16_hi v[6:7], v9, off offset:96
	s_waitcnt lgkmcnt(0)
; __device__ __forceinline__ unsigned f2bf(float f) { unsigned u = __builtin_bit_cast(unsigned, f); return (u + 0x7fffu + ((u >> 16) & 1u)) >> 16; }
; template <bool SAMPLE> __device__ __forceinline__ void attn_unit16(const Ctx& c, LAS unsigned char* lds, int b, int h, int qb, int wave_s) {
;     ...
;             for (int i = 0; i < 4; ++i) {
;                 float ss = 0.f;
; #pragma unroll
;                 for (int et = 0; et < 8; ++et) { o[qt][et][i] -= X[(g * 64 + qt * 32 + et * 4 + i) * 64 + lane2]; ss += o[qt][et][i] * o[qt][et][i]; }
;                 ss += __shfl_xor(ss, 1); ss += __shfl_xor(ss, 2); ss += __shfl_xor(ss, 4); ss += __shfl_xor(ss, 8);
;                 const float rstd = 1.f / sqrtf(ss * (1.f / 128.f) + 1e-5f);
;                 const int ql = 16 * qt + 4 * q4b + i;
;                 const size_t row = SAMPLE ? (size_t)ROW_S0 + b * 16 + ql : (size_t)b * SEQ + tq0 + ql;
; #pragma unroll
;                 for (int et = 0; et < 8; ++et) Y[row * D + h * 128 + 16 * et + c16b] = (bf16)f2bf(o[qt][et][i] * rstd * sg[et]);
	s_nop 1
	v_add_f32_dpp v10, v13, v13 quad_perm:[1,0,3,2] row_mask:0xf bank_mask:0xf
	v_mul_f32_e32 v9, v20, v8
	v_mul_f32_e32 v9, v51, v9
	v_bfe_u32 v16, v9, 16, 1
	v_add3_u32 v9, v9, v16, s76
	s_waitcnt lgkmcnt(0)
	s_nop 1
	v_add_f32_dpp v10, v10, v10 quad_perm:[2,3,0,1] row_mask:0xf bank_mask:0xf
	global_store_short_d16_hi v[6:7], v9, off offset:128
	v_mul_f32_e32 v9, v18, v8
	v_mul_f32_e32 v9, v50, v9
	v_bfe_u32 v16, v9, 16, 1
	v_add3_u32 v9, v9, v16, s76
	global_store_short_d16_hi v[6:7], v9, off offset:160
	s_waitcnt lgkmcnt(0)
	s_nop 1
	v_add_f32_dpp v9, v10, v10 row_half_mirror row_mask:0xf bank_mask:0xf
	v_mul_f32_e32 v13, v24, v8
	v_mul_f32_e32 v13, v49, v13
	v_bfe_u32 v16, v13, 16, 1
	v_add3_u32 v13, v13, v16, s76
	s_waitcnt lgkmcnt(0)
	s_nop 1
	v_add_f32_dpp v9, v9, v9 row_mirror row_mask:0xf bank_mask:0xf
	v_fmamk_f32 v9, v9, 0x3c000000, v205
	v_mul_f32_e32 v10, 0x4f800000, v9
	v_cmp_gt_f32_e32 vcc, s75, v9
	global_store_short_d16_hi v[6:7], v13, off offset:192
	v_mul_f32_e32 v8, v22, v8
	v_cndmask_b32_e32 v9, v9, v10, vcc
	v_sqrt_f32_e32 v10, v9
	v_mul_f32_e32 v8, v0, v8
	v_add_u32_e32 v13, -1, v10
	v_fma_f32 v16, -v13, v10, v9
	v_cmp_ge_f32_e64 s[0:1], 0, v16
	v_add_u32_e32 v16, 1, v10
	s_nop 0
	v_cndmask_b32_e64 v13, v10, v13, s[0:1]
	v_fma_f32 v10, -v16, v10, v9
	v_cmp_lt_f32_e64 s[0:1], 0, v10
	s_nop 1
	v_cndmask_b32_e64 v10, v13, v16, s[0:1]
	v_mul_f32_e32 v13, 0x37800000, v10
	v_cndmask_b32_e32 v10, v10, v13, vcc
	v_cmp_class_f32_e32 vcc, v9, v206
	v_bfe_u32 v16, v8, 16, 1
	v_add3_u32 v8, v8, v16, s76
	v_cndmask_b32_e32 v9, v10, v9, vcc
	v_div_scale_f32 v10, s[0:1], v9, v9, 1.0
	v_rcp_f32_e32 v13, v10
	global_store_short_d16_hi v[6:7], v8, off offset:224
	v_fma_f32 v6, -v10, v13, 1.0
	v_fmac_f32_e32 v13, v6, v13
	v_div_scale_f32 v6, vcc, 1.0, v9, 1.0
	v_mul_f32_e32 v7, v6, v13
	v_fma_f32 v8, -v10, v7, v6
	v_fmac_f32_e32 v7, v8, v13
	v_fma_f32 v6, -v10, v7, v6
	v_div_fmas_f32 v6, v6, v13, v7
	v_div_fixup_f32 v79, v6, v9, 1.0
	v_mul_f32_e32 v8, v12, v79
	v_or_b32_e32 v6, 3, v4
	v_mov_b32_e32 v7, s17
	v_mul_f32_e32 v8, v62, v8
	v_lshlrev_b64 v[6:7], 11, v[6:7]
	v_bfe_u32 v9, v8, 16, 1
	v_lshl_add_u64 v[6:7], v[2:3], 0, v[6:7]
	v_add3_u32 v8, v8, v9, s76
	global_store_short_d16_hi v[6:7], v8, off
	v_mul_f32_e32 v8, v11, v79
	v_mul_f32_e32 v8, v55, v8
	v_bfe_u32 v9, v8, 16, 1
	v_add3_u32 v8, v8, v9, s76
	global_store_short_d16_hi v[6:7], v8, off offset:32
	v_mul_f32_e32 v8, v14, v79
	v_mul_f32_e32 v8, v54, v8
	v_bfe_u32 v9, v8, 16, 1
	v_add3_u32 v8, v8, v9, s76
	global_store_short_d16_hi v[6:7], v8, off offset:64
	v_mul_f32_e32 v8, v15, v79
	v_mul_f32_e32 v80, v53, v8
	ds_read2st64_b32 v[8:9], v64 offset0:32 offset1:33
	ds_read2st64_b32 v[10:11], v64 offset0:36 offset1:37
	ds_read2st64_b32 v[12:13], v64 offset0:38 offset1:39
	ds_read2st64_b32 v[14:15], v64 offset0:34 offset1:35
	ds_read2st64_b32 v[66:67], v64 offset0:40 offset1:41
	v_bfe_u32 v81, v80, 16, 1
	s_waitcnt lgkmcnt(4)
	v_sub_f32_e32 v8, v63, v8
	s_waitcnt lgkmcnt(3)
	v_sub_f32_e32 v10, v68, v10
	ds_read2st64_b32 v[68:69], v64 offset0:44 offset1:45
	ds_read2st64_b32 v[16:17], v64 offset0:46 offset1:47
	ds_read2st64_b32 v[18:19], v64 offset0:42 offset1:43
	s_waitcnt lgkmcnt(3)
	v_sub_f32_e32 v66, v61, v66
	v_mul_f32_e32 v63, v10, v10
	s_waitcnt lgkmcnt(2)
	v_sub_f32_e32 v68, v60, v68
	ds_read2st64_b32 v[60:61], v64 offset0:48 offset1:49
	ds_read2st64_b32 v[70:71], v64 offset0:52 offset1:53
	ds_read2st64_b32 v[20:21], v64 offset0:54 offset1:55
	ds_read2st64_b32 v[22:23], v64 offset0:50 offset1:51
	ds_read2st64_b32 v[72:73], v64 offset0:56 offset1:57
	v_fmac_f32_e32 v63, v8, v8
	v_fmac_f32_e32 v63, v66, v66
	v_fmac_f32_e32 v63, v68, v68
	s_waitcnt lgkmcnt(4)
	v_sub_f32_e32 v60, v27, v60
	s_waitcnt lgkmcnt(3)
	v_sub_f32_e32 v70, v26, v70
	ds_read2st64_b32 v[74:75], v64 offset0:60 offset1:61
	ds_read2st64_b32 v[24:25], v64 offset0:62 offset1:63
	ds_read2st64_b32 v[26:27], v64 offset0:58 offset1:59
	v_fmac_f32_e32 v63, v60, v60
	v_fmac_f32_e32 v63, v70, v70
	s_waitcnt lgkmcnt(3)
	v_sub_f32_e32 v59, v59, v72
	v_fmac_f32_e32 v63, v59, v59
	s_waitcnt lgkmcnt(2)
	v_sub_f32_e32 v58, v58, v74
	v_fmac_f32_e32 v63, v58, v58
	v_mul_f32_e32 v65, v65, v79
	v_add3_u32 v72, v80, v81, s76
	v_mul_f32_e32 v65, v51, v65
	global_store_short_d16_hi v[6:7], v72, off offset:96
	s_waitcnt lgkmcnt(0)
	s_nop 1
	v_add_f32_dpp v63, v63, v63 quad_perm:[1,0,3,2] row_mask:0xf bank_mask:0xf
	v_bfe_u32 v72, v65, 16, 1
	v_add3_u32 v65, v65, v72, s76
	global_store_short_d16_hi v[6:7], v65, off offset:128
	v_mul_f32_e32 v65, v76, v79
	s_waitcnt lgkmcnt(0)
	s_nop 1
	v_add_f32_dpp v63, v63, v63 quad_perm:[2,3,0,1] row_mask:0xf bank_mask:0xf
	v_mul_f32_e32 v65, v50, v65
	v_bfe_u32 v72, v65, 16, 1
	v_add3_u32 v65, v65, v72, s76
	global_store_short_d16_hi v[6:7], v65, off offset:160
	s_waitcnt lgkmcnt(0)
	s_nop 1
	v_add_f32_dpp v63, v63, v63 row_half_mirror row_mask:0xf bank_mask:0xf
	v_mul_f32_e32 v65, v77, v79
	v_mul_f32_e32 v65, v49, v65
	v_bfe_u32 v72, v65, 16, 1
	v_add3_u32 v65, v65, v72, s76
	s_waitcnt lgkmcnt(0)
; __device__ __forceinline__ unsigned f2bf(float f) { unsigned u = __builtin_bit_cast(unsigned, f); return (u + 0x7fffu + ((u >> 16) & 1u)) >> 16; }
; template <bool SAMPLE> __device__ __forceinline__ void attn_unit16(const Ctx& c, LAS unsigned char* lds, int b, int h, int qb, int wave_s) {
;     ...
;             for (int i = 0; i < 4; ++i) {
;                 float ss = 0.f;
; #pragma unroll
;                 for (int et = 0; et < 8; ++et) { o[qt][et][i] -= X[(g * 64 + qt * 32 + et * 4 + i) * 64 + lane2]; ss += o[qt][et][i] * o[qt][et][i]; }
;                 ss += __shfl_xor(ss, 1); ss += __shfl_xor(ss, 2); ss += __shfl_xor(ss, 4); ss += __shfl_xor(ss, 8);
;                 const float rstd = 1.f / sqrtf(ss * (1.f / 128.f) + 1e-5f);
;                 const int ql = 16 * qt + 4 * q4b + i;
;                 const size_t row = SAMPLE ? (size_t)ROW_S0 + b * 16 + ql : (size_t)b * SEQ + tq0 + ql;
; #pragma unroll
;                 for (int et = 0; et < 8; ++et) Y[row * D + h * 128 + 16 * et + c16b] = (bf16)f2bf(o[qt][et][i] * rstd * sg[et]);
	s_nop 1
	v_add_f32_dpp v63, v63, v63 row_mirror row_mask:0xf bank_mask:0xf
	v_fmamk_f32 v63, v63, 0x3c000000, v205
	v_mul_f32_e32 v64, 0x4f800000, v63
	v_cmp_gt_f32_e32 vcc, s75, v63
	global_store_short_d16_hi v[6:7], v65, off offset:192
	v_mul_f32_e32 v65, v78, v79
	v_cndmask_b32_e32 v63, v63, v64, vcc
	v_sqrt_f32_e32 v64, v63
	v_mul_f32_e32 v65, v0, v65
	v_sub_f32_e32 v11, v52, v11
	v_sub_f32_e32 v9, v48, v9
	v_add_u32_e32 v72, -1, v64
	v_fma_f32 v74, -v72, v64, v63
	v_cmp_ge_f32_e64 s[0:1], 0, v74
	v_add_u32_e32 v74, 1, v64
	v_mul_f32_e32 v48, v11, v11
	v_cndmask_b32_e64 v72, v64, v72, s[0:1]
	v_fma_f32 v64, -v74, v64, v63
	v_cmp_lt_f32_e64 s[0:1], 0, v64
	v_fmac_f32_e32 v48, v9, v9
	v_sub_f32_e32 v45, v45, v67
	v_cndmask_b32_e64 v64, v72, v74, s[0:1]
	v_mul_f32_e32 v72, 0x37800000, v64
	v_cndmask_b32_e32 v64, v64, v72, vcc
	v_cmp_class_f32_e32 vcc, v63, v206
	v_bfe_u32 v74, v65, 16, 1
	v_add3_u32 v65, v65, v74, s76
	v_cndmask_b32_e32 v63, v64, v63, vcc
	v_div_scale_f32 v64, s[0:1], v63, v63, 1.0
	v_rcp_f32_e32 v72, v64
	global_store_short_d16_hi v[6:7], v65, off offset:224
	v_fmac_f32_e32 v48, v45, v45
	v_sub_f32_e32 v44, v44, v69
	v_fma_f32 v6, -v64, v72, 1.0
	v_fmac_f32_e32 v72, v6, v72
	v_div_scale_f32 v6, vcc, 1.0, v63, 1.0
	v_mul_f32_e32 v7, v6, v72
	v_fma_f32 v65, -v64, v7, v6
	v_fmac_f32_e32 v7, v65, v72
	v_fma_f32 v6, -v64, v7, v6
	v_div_fmas_f32 v6, v6, v72, v7
	v_div_fixup_f32 v63, v6, v63, 1.0
	v_mul_f32_e32 v8, v8, v63
	v_or_b32_e32 v6, 16, v4
	v_mov_b32_e32 v7, s17
	v_mul_f32_e32 v8, v62, v8
	v_lshlrev_b64 v[6:7], 11, v[6:7]
	v_bfe_u32 v64, v8, 16, 1
	v_lshl_add_u64 v[6:7], v[2:3], 0, v[6:7]
	v_add3_u32 v8, v8, v64, s76
	global_store_short_d16_hi v[6:7], v8, off
	v_mul_f32_e32 v8, v10, v63
	v_mul_f32_e32 v8, v55, v8
	v_fmac_f32_e32 v48, v44, v44
	v_sub_f32_e32 v52, v57, v61
	v_bfe_u32 v10, v8, 16, 1
	v_fmac_f32_e32 v48, v52, v52
	v_sub_f32_e32 v56, v56, v71
	v_add3_u32 v8, v8, v10, s76
	v_fmac_f32_e32 v48, v56, v56
	v_sub_f32_e32 v47, v47, v73
	global_store_short_d16_hi v[6:7], v8, off offset:32
	v_mul_f32_e32 v8, v66, v63
	v_fmac_f32_e32 v48, v47, v47
	v_sub_f32_e32 v46, v46, v75
	v_mul_f32_e32 v8, v54, v8
	v_fmac_f32_e32 v48, v46, v46
	v_bfe_u32 v10, v8, 16, 1
	v_add3_u32 v8, v8, v10, s76
	global_store_short_d16_hi v[6:7], v8, off offset:64
	v_mul_f32_e32 v8, v68, v63
	v_mul_f32_e32 v8, v53, v8
	v_bfe_u32 v10, v8, 16, 1
	v_add3_u32 v8, v8, v10, s76
	s_waitcnt lgkmcnt(0)
	s_nop 1
	v_add_f32_dpp v10, v48, v48 quad_perm:[1,0,3,2] row_mask:0xf bank_mask:0xf
	global_store_short_d16_hi v[6:7], v8, off offset:96
	v_mul_f32_e32 v8, v60, v63
	v_mul_f32_e32 v8, v51, v8
	v_bfe_u32 v57, v8, 16, 1
	s_waitcnt lgkmcnt(0)
	s_nop 1
	v_add_f32_dpp v10, v10, v10 quad_perm:[2,3,0,1] row_mask:0xf bank_mask:0xf
	v_add3_u32 v8, v8, v57, s76
	global_store_short_d16_hi v[6:7], v8, off offset:128
	v_mul_f32_e32 v8, v70, v63
	v_mul_f32_e32 v8, v50, v8
	v_bfe_u32 v57, v8, 16, 1
	v_add3_u32 v8, v8, v57, s76
	global_store_short_d16_hi v[6:7], v8, off offset:160
	s_waitcnt lgkmcnt(0)
	s_nop 1
	v_add_f32_dpp v8, v10, v10 row_half_mirror row_mask:0xf bank_mask:0xf
	v_mul_f32_e32 v48, v59, v63
	v_mul_f32_e32 v48, v49, v48
	v_bfe_u32 v57, v48, 16, 1
	v_add3_u32 v48, v48, v57, s76
	s_waitcnt lgkmcnt(0)
	s_nop 1
	v_add_f32_dpp v8, v8, v8 row_mirror row_mask:0xf bank_mask:0xf
	v_fmamk_f32 v8, v8, 0x3c000000, v205
	v_mul_f32_e32 v10, 0x4f800000, v8
	v_cmp_gt_f32_e32 vcc, s75, v8
	global_store_short_d16_hi v[6:7], v48, off offset:192
	v_mul_f32_e32 v48, v58, v63
	v_cndmask_b32_e32 v8, v8, v10, vcc
	v_sqrt_f32_e32 v10, v8
	v_mul_f32_e32 v48, v0, v48
	v_sub_f32_e32 v12, v41, v12
	v_sub_f32_e32 v18, v37, v18
	v_add_u32_e32 v57, -1, v10
	v_fma_f32 v58, -v57, v10, v8
	v_cmp_ge_f32_e64 s[0:1], 0, v58
	v_add_u32_e32 v58, 1, v10
	v_sub_f32_e32 v16, v36, v16
	v_cndmask_b32_e64 v57, v10, v57, s[0:1]
	v_fma_f32 v10, -v58, v10, v8
	v_cmp_lt_f32_e64 s[0:1], 0, v10
	v_sub_f32_e32 v22, v43, v22
	v_sub_f32_e32 v20, v42, v20
	v_cndmask_b32_e64 v10, v57, v58, s[0:1]
	v_mul_f32_e32 v57, 0x37800000, v10
	v_cndmask_b32_e32 v10, v10, v57, vcc
	v_cmp_class_f32_e32 vcc, v8, v206
	v_bfe_u32 v58, v48, 16, 1
	v_add3_u32 v48, v48, v58, s76
	v_cndmask_b32_e32 v8, v10, v8, vcc
	v_div_scale_f32 v10, s[0:1], v8, v8, 1.0
	v_rcp_f32_e32 v57, v10
	global_store_short_d16_hi v[6:7], v48, off offset:224
	v_sub_f32_e32 v26, v39, v26
	v_sub_f32_e32 v24, v38, v24
	v_fma_f32 v6, -v10, v57, 1.0
	v_fmac_f32_e32 v57, v6, v57
	v_div_scale_f32 v6, vcc, 1.0, v8, 1.0
	v_mul_f32_e32 v7, v6, v57
	v_fma_f32 v48, -v10, v7, v6
	v_fmac_f32_e32 v7, v48, v57
	v_fma_f32 v6, -v10, v7, v6
	v_div_fmas_f32 v6, v6, v57, v7
	v_div_fixup_f32 v8, v6, v8, 1.0
	v_mul_f32_e32 v9, v9, v8
	v_or_b32_e32 v6, 17, v4
	v_mov_b32_e32 v7, s17
	v_mul_f32_e32 v9, v62, v9
	v_lshlrev_b64 v[6:7], 11, v[6:7]
	v_bfe_u32 v10, v9, 16, 1
	v_lshl_add_u64 v[6:7], v[2:3], 0, v[6:7]
	v_add3_u32 v9, v9, v10, s76
	global_store_short_d16_hi v[6:7], v9, off
	v_mul_f32_e32 v9, v11, v8
	v_sub_f32_e32 v11, v40, v14
	v_mul_f32_e32 v14, v12, v12
	v_fmac_f32_e32 v14, v11, v11
	v_fmac_f32_e32 v14, v18, v18
	v_mul_f32_e32 v9, v55, v9
	v_fmac_f32_e32 v14, v16, v16
	v_bfe_u32 v10, v9, 16, 1
	v_fmac_f32_e32 v14, v22, v22
	v_add3_u32 v9, v9, v10, s76
	v_fmac_f32_e32 v14, v20, v20
	global_store_short_d16_hi v[6:7], v9, off offset:32
	v_mul_f32_e32 v9, v45, v8
	v_fmac_f32_e32 v14, v26, v26
	v_mul_f32_e32 v9, v54, v9
	v_fmac_f32_e32 v14, v24, v24
	v_bfe_u32 v10, v9, 16, 1
	v_add3_u32 v9, v9, v10, s76
	global_store_short_d16_hi v[6:7], v9, off offset:64
	v_mul_f32_e32 v9, v44, v8
	v_mul_f32_e32 v9, v53, v9
	v_bfe_u32 v10, v9, 16, 1
	v_add3_u32 v9, v9, v10, s76
	s_waitcnt lgkmcnt(0)
; __device__ __forceinline__ unsigned f2bf(float f) { unsigned u = __builtin_bit_cast(unsigned, f); return (u + 0x7fffu + ((u >> 16) & 1u)) >> 16; }
; template <bool SAMPLE> __device__ __forceinline__ void attn_unit16(const Ctx& c, LAS unsigned char* lds, int b, int h, int qb, int wave_s) {
;     ...
;             for (int i = 0; i < 4; ++i) {
;                 float ss = 0.f;
; #pragma unroll
;                 for (int et = 0; et < 8; ++et) { o[qt][et][i] -= X[(g * 64 + qt * 32 + et * 4 + i) * 64 + lane2]; ss += o[qt][et][i] * o[qt][et][i]; }
;                 ss += __shfl_xor(ss, 1); ss += __shfl_xor(ss, 2); ss += __shfl_xor(ss, 4); ss += __shfl_xor(ss, 8);
;                 const float rstd = 1.f / sqrtf(ss * (1.f / 128.f) + 1e-5f);
;                 const int ql = 16 * qt + 4 * q4b + i;
;                 const size_t row = SAMPLE ? (size_t)ROW_S0 + b * 16 + ql : (size_t)b * SEQ + tq0 + ql;
; #pragma unroll
;                 for (int et = 0; et < 8; ++et) Y[row * D + h * 128 + 16 * et + c16b] = (bf16)f2bf(o[qt][et][i] * rstd * sg[et]);
	s_nop 1
	v_add_f32_dpp v10, v14, v14 quad_perm:[1,0,3,2] row_mask:0xf bank_mask:0xf
	global_store_short_d16_hi v[6:7], v9, off offset:96
	v_mul_f32_e32 v9, v52, v8
	v_mul_f32_e32 v9, v51, v9
	v_bfe_u32 v36, v9, 16, 1
	s_waitcnt lgkmcnt(0)
	s_nop 1
	v_add_f32_dpp v10, v10, v10 quad_perm:[2,3,0,1] row_mask:0xf bank_mask:0xf
	v_add3_u32 v9, v9, v36, s76
	global_store_short_d16_hi v[6:7], v9, off offset:128
	v_mul_f32_e32 v9, v56, v8
	v_mul_f32_e32 v9, v50, v9
	v_bfe_u32 v36, v9, 16, 1
	v_add3_u32 v9, v9, v36, s76
	global_store_short_d16_hi v[6:7], v9, off offset:160
	s_waitcnt lgkmcnt(0)
	s_nop 1
	v_add_f32_dpp v9, v10, v10 row_half_mirror row_mask:0xf bank_mask:0xf
	v_mul_f32_e32 v14, v47, v8
	v_mul_f32_e32 v14, v49, v14
	v_bfe_u32 v36, v14, 16, 1
	v_add3_u32 v14, v14, v36, s76
	s_waitcnt lgkmcnt(0)
	s_nop 1
	v_add_f32_dpp v9, v9, v9 row_mirror row_mask:0xf bank_mask:0xf
	v_fmamk_f32 v9, v9, 0x3c000000, v205
	v_mul_f32_e32 v10, 0x4f800000, v9
	v_cmp_gt_f32_e32 vcc, s75, v9
	global_store_short_d16_hi v[6:7], v14, off offset:192
	v_mul_f32_e32 v8, v46, v8
	v_cndmask_b32_e32 v9, v9, v10, vcc
	v_sqrt_f32_e32 v10, v9
	v_mul_f32_e32 v8, v0, v8
	v_add_u32_e32 v14, -1, v10
	v_fma_f32 v36, -v14, v10, v9
	v_cmp_ge_f32_e64 s[0:1], 0, v36
	v_add_u32_e32 v36, 1, v10
	s_nop 0
	v_cndmask_b32_e64 v14, v10, v14, s[0:1]
	v_fma_f32 v10, -v36, v10, v9
	v_cmp_lt_f32_e64 s[0:1], 0, v10
	s_nop 1
	v_cndmask_b32_e64 v10, v14, v36, s[0:1]
	v_mul_f32_e32 v14, 0x37800000, v10
	v_cndmask_b32_e32 v10, v10, v14, vcc
	v_cmp_class_f32_e32 vcc, v9, v206
	v_bfe_u32 v36, v8, 16, 1
	v_add3_u32 v8, v8, v36, s76
	v_cndmask_b32_e32 v9, v10, v9, vcc
	v_div_scale_f32 v10, s[0:1], v9, v9, 1.0
	v_rcp_f32_e32 v14, v10
	global_store_short_d16_hi v[6:7], v8, off offset:224
	v_fma_f32 v6, -v10, v14, 1.0
	v_fmac_f32_e32 v14, v6, v14
	v_div_scale_f32 v6, vcc, 1.0, v9, 1.0
	v_mul_f32_e32 v7, v6, v14
	v_fma_f32 v8, -v10, v7, v6
	v_fmac_f32_e32 v7, v8, v14
	v_fma_f32 v6, -v10, v7, v6
	v_div_fmas_f32 v6, v6, v14, v7
	v_div_fixup_f32 v8, v6, v9, 1.0
	v_mul_f32_e32 v9, v11, v8
	v_or_b32_e32 v6, 18, v4
	v_mov_b32_e32 v7, s17
	v_mul_f32_e32 v9, v62, v9
	v_lshlrev_b64 v[6:7], 11, v[6:7]
	v_bfe_u32 v10, v9, 16, 1
	v_lshl_add_u64 v[6:7], v[2:3], 0, v[6:7]
	v_add3_u32 v9, v9, v10, s76
	global_store_short_d16_hi v[6:7], v9, off
	v_mul_f32_e32 v9, v12, v8
	v_mul_f32_e32 v9, v55, v9
	v_bfe_u32 v10, v9, 16, 1
	v_add3_u32 v9, v9, v10, s76
	global_store_short_d16_hi v[6:7], v9, off offset:32
	v_mul_f32_e32 v9, v18, v8
	v_sub_f32_e32 v12, v35, v13
	v_mul_f32_e32 v9, v54, v9
	v_sub_f32_e32 v11, v34, v15
	v_mul_f32_e32 v13, v12, v12
	v_bfe_u32 v10, v9, 16, 1
	v_fmac_f32_e32 v13, v11, v11
	v_sub_f32_e32 v14, v33, v19
	v_add3_u32 v9, v9, v10, s76
	v_fmac_f32_e32 v13, v14, v14
	v_sub_f32_e32 v15, v32, v17
	global_store_short_d16_hi v[6:7], v9, off offset:64
	v_mul_f32_e32 v9, v16, v8
	v_fmac_f32_e32 v13, v15, v15
	v_sub_f32_e32 v16, v31, v23
	v_fmac_f32_e32 v13, v16, v16
	v_sub_f32_e32 v17, v30, v21
	v_fmac_f32_e32 v13, v17, v17
	v_sub_f32_e32 v18, v29, v27
	v_fmac_f32_e32 v13, v18, v18
	v_sub_f32_e32 v19, v28, v25
	v_fmac_f32_e32 v13, v19, v19
	v_mul_f32_e32 v9, v53, v9
	v_bfe_u32 v10, v9, 16, 1
	v_add3_u32 v9, v9, v10, s76
	global_store_short_d16_hi v[6:7], v9, off offset:96
	s_waitcnt lgkmcnt(0)
	s_nop 1
	v_add_f32_dpp v10, v13, v13 quad_perm:[1,0,3,2] row_mask:0xf bank_mask:0xf
	v_mul_f32_e32 v9, v22, v8
	v_mul_f32_e32 v9, v51, v9
	v_bfe_u32 v21, v9, 16, 1
	v_add3_u32 v9, v9, v21, s76
	s_waitcnt lgkmcnt(0)
	s_nop 1
	v_add_f32_dpp v10, v10, v10 quad_perm:[2,3,0,1] row_mask:0xf bank_mask:0xf
	global_store_short_d16_hi v[6:7], v9, off offset:128
	v_mul_f32_e32 v9, v20, v8
	v_mul_f32_e32 v9, v50, v9
	v_bfe_u32 v20, v9, 16, 1
	v_add3_u32 v9, v9, v20, s76
	global_store_short_d16_hi v[6:7], v9, off offset:160
	s_waitcnt lgkmcnt(0)
	s_nop 1
	v_add_f32_dpp v9, v10, v10 row_half_mirror row_mask:0xf bank_mask:0xf
	v_mul_f32_e32 v13, v26, v8
	v_mul_f32_e32 v13, v49, v13
	v_bfe_u32 v20, v13, 16, 1
	v_add3_u32 v13, v13, v20, s76
	s_waitcnt lgkmcnt(0)
	s_nop 1
	v_add_f32_dpp v9, v9, v9 row_mirror row_mask:0xf bank_mask:0xf
	v_fmamk_f32 v9, v9, 0x3c000000, v205
	v_mul_f32_e32 v10, 0x4f800000, v9
	v_cmp_gt_f32_e32 vcc, s75, v9
	global_store_short_d16_hi v[6:7], v13, off offset:192
	v_mul_f32_e32 v8, v24, v8
	v_cndmask_b32_e32 v9, v9, v10, vcc
	v_sqrt_f32_e32 v10, v9
	v_mul_f32_e32 v8, v0, v8
	v_or_b32_e32 v4, 19, v4
	v_lshlrev_b64 v[4:5], 11, v[4:5]
	v_add_u32_e32 v13, -1, v10
	v_fma_f32 v20, -v13, v10, v9
	v_cmp_ge_f32_e64 s[0:1], 0, v20
	v_add_u32_e32 v20, 1, v10
	v_lshl_add_u64 v[2:3], v[2:3], 0, v[4:5]
	v_cndmask_b32_e64 v13, v10, v13, s[0:1]
	v_fma_f32 v10, -v20, v10, v9
	v_cmp_lt_f32_e64 s[0:1], 0, v10
	s_nop 1
	v_cndmask_b32_e64 v10, v13, v20, s[0:1]
	v_mul_f32_e32 v13, 0x37800000, v10
	v_cndmask_b32_e32 v10, v10, v13, vcc
	v_cmp_class_f32_e32 vcc, v9, v206
	v_bfe_u32 v20, v8, 16, 1
	v_add3_u32 v8, v8, v20, s76
	v_cndmask_b32_e32 v9, v10, v9, vcc
	v_div_scale_f32 v10, s[0:1], v9, v9, 1.0
	v_rcp_f32_e32 v13, v10
	global_store_short_d16_hi v[6:7], v8, off offset:224
	v_fma_f32 v6, -v10, v13, 1.0
	v_fmac_f32_e32 v13, v6, v13
	v_div_scale_f32 v6, vcc, 1.0, v9, 1.0
	v_mul_f32_e32 v7, v6, v13
	v_fma_f32 v8, -v10, v7, v6
	v_fmac_f32_e32 v7, v8, v13
	v_fma_f32 v6, -v10, v7, v6
	v_div_fmas_f32 v6, v6, v13, v7
	v_div_fixup_f32 v6, v6, v9, 1.0
	v_mul_f32_e32 v4, v11, v6
	v_mul_f32_e32 v4, v62, v4
	v_bfe_u32 v5, v4, 16, 1
	v_add3_u32 v4, v4, v5, s76
	global_store_short_d16_hi v[2:3], v4, off
	v_mul_f32_e32 v4, v12, v6
	v_mul_f32_e32 v4, v55, v4
	v_bfe_u32 v5, v4, 16, 1
	v_add3_u32 v4, v4, v5, s76
	global_store_short_d16_hi v[2:3], v4, off offset:32
	v_mul_f32_e32 v4, v14, v6
	v_mul_f32_e32 v4, v54, v4
	v_bfe_u32 v5, v4, 16, 1
	v_add3_u32 v4, v4, v5, s76
	global_store_short_d16_hi v[2:3], v4, off offset:64
	v_mul_f32_e32 v4, v15, v6
	v_mul_f32_e32 v4, v53, v4
	v_bfe_u32 v5, v4, 16, 1
	v_add3_u32 v4, v4, v5, s76
	global_store_short_d16_hi v[2:3], v4, off offset:96
	v_mul_f32_e32 v4, v16, v6
	v_mul_f32_e32 v4, v51, v4
	v_bfe_u32 v5, v4, 16, 1
	v_add3_u32 v4, v4, v5, s76
	global_store_short_d16_hi v[2:3], v4, off offset:128
	v_mul_f32_e32 v4, v17, v6
	v_mul_f32_e32 v4, v50, v4
	v_bfe_u32 v5, v4, 16, 1
	v_add3_u32 v4, v4, v5, s76
	global_store_short_d16_hi v[2:3], v4, off offset:160
	v_mul_f32_e32 v4, v18, v6
	v_mul_f32_e32 v4, v49, v4
	v_bfe_u32 v5, v4, 16, 1
	v_add3_u32 v4, v4, v5, s76
	global_store_short_d16_hi v[2:3], v4, off offset:192
	v_mul_f32_e32 v4, v19, v6
	v_mul_f32_e32 v0, v0, v4
	v_bfe_u32 v4, v0, 16, 1
	v_add3_u32 v0, v0, v4, s76
	global_store_short_d16_hi v[2:3], v0, off offset:224
